# added: xbc conv row prefetch one iteration ahead; P f32-to-bf16 conversion 4 rows in flight; on top of final-norm pipelining, batched weight transposes, SSD read pipelining, attention loop reorder
# speedup vs baseline: 1.0159x; 1.0031x over previous
; __device__ __forceinline__ unsigned cvtpk(float lo, float hi) { f32x2 v = {lo, hi}; bf16x2_t b = __builtin_convertvector(v, bf16x2_t); return __builtin_bit_cast(unsigned, b); }
; __device__ __forceinline__ float siluf_(float x) { return x * __builtin_amdgcn_rcpf(1.f + __builtin_amdgcn_exp2f(x * -LOG2E)); }
; __device__ __forceinline__ void xbc_conv_item(CP& P, int L, int item) {
;     ...
;     for (int r = 0; r < 32; ++r) {
; #pragma unroll
;         for (int j = 0; j < 4; ++j) win[j] = win[j + 1];
;         { const int t = r0 + r + 2; win[4] = (t >= s0 && t < s1) ? *(const u32x4*)(src + (size_t)t * PROJ_PITCH) : (u32x4){0u, 0u, 0u, 0u}; }
;         float a[8];
; #pragma unroll
;         for (int k = 0; k < 8; ++k) a[k] = bs[k];
; #pragma unroll
;         for (int j = 0; j < 5; ++j) { float x[8]; unpack8(win[j], x);
; #pragma unroll
;             for (int k = 0; k < 8; ++k) a[k] += x[k] * w[j][k]; }
; #pragma unroll
;         for (int k = 0; k < 8; ++k) a[k] = siluf_(a[k]);
;         u32x4 o; o.x = cvtpk(a[0], a[1]); o.y = cvtpk(a[2], a[3]); o.z = cvtpk(a[4], a[5]); o.w = cvtpk(a[6], a[7]);
;         *(u32x4*)(xbc + (size_t)(r0 + r) * XBC_W + c8) = o;
;     }
; __global__ void __launch_bounds__(512, 2) hybrid_fwd(Params P0) {
;     ...
;             for (int it = bx; it < (T / 32 + 2) / 3; it += G) xbc_conv_item(P, L, it);
.LBB0_118:
	s_waitcnt vmcnt(0)
	s_or_b64 exec, exec, s[8:9]
	v_readlane_b32 s0, v252, 53
	s_add_i32 s14, s14, s0
	v_readlane_b32 s0, v252, 54
	s_add_i32 s15, s15, s82
	s_add_i32 s2, s2, s0
	s_cmpk_gt_i32 s15, 0x1aa
	s_cbranch_scc1 .LBB0_138

; __device__ __forceinline__ unsigned cvtpk(float lo, float hi) { f32x2 v = {lo, hi}; bf16x2_t b = __builtin_convertvector(v, bf16x2_t); return __builtin_bit_cast(unsigned, b); }
; __device__ __forceinline__ float siluf_(float x) { return x * __builtin_amdgcn_rcpf(1.f + __builtin_amdgcn_exp2f(x * -LOG2E)); }
; __device__ __forceinline__ void xbc_conv_item(CP& P, int L, int item) {
;     ...
;     const bf16_t* src = proj + XBCOFF + c8;
;     u32x4 win[5];
; #pragma unroll
;     for (int j = 0; j < 4; ++j) { const int t = r0 - 2 + j; win[j + 1] = (t >= s0 && t < s1) ? *(const u32x4*)(src + (size_t)t * PROJ_PITCH) : (u32x4){0u, 0u, 0u, 0u}; }
; #pragma unroll 4
;     for (int r = 0; r < 32; ++r) {
; #pragma unroll
;         for (int j = 0; j < 4; ++j) win[j] = win[j + 1];
;         { const int t = r0 + r + 2; win[4] = (t >= s0 && t < s1) ? *(const u32x4*)(src + (size_t)t * PROJ_PITCH) : (u32x4){0u, 0u, 0u, 0u}; }
;         float a[8];
; #pragma unroll
;         for (int k = 0; k < 8; ++k) a[k] = bs[k];
; #pragma unroll
;         for (int j = 0; j < 5; ++j) { float x[8]; unpack8(win[j], x);
; #pragma unroll
;             for (int k = 0; k < 8; ++k) a[k] += x[k] * w[j][k]; }
; #pragma unroll
;         for (int k = 0; k < 8; ++k) a[k] = siluf_(a[k]);
;         u32x4 o; o.x = cvtpk(a[0], a[1]); o.y = cvtpk(a[2], a[3]); o.z = cvtpk(a[4], a[5]); o.w = cvtpk(a[6], a[7]);
;         *(u32x4*)(xbc + (size_t)(r0 + r) * XBC_W + c8) = o;
.LBB0_128:
	s_or_b64 exec, exec, s[0:1]
	v_lshl_add_u32 v108, v48, 5, s14
	v_lshlrev_b64 v[70:71], 1, v[52:53]
	v_add_lshl_u32 v48, v48, s2, 5
	v_mov_b64_e32 v[52:53], s[26:27]
	v_mad_i64_i32 v[74:75], s[0:1], v48, s44, v[52:53]
	v_mad_i64_i32 v[76:77], s[0:1], v48, s45, v[52:53]
	v_lshl_add_u64 v[140:141], v[76:77], 0, v[70:71]
	v_add_u32_e32 v138, 2, v108
	v_cmp_ge_i32_e32 vcc, v138, v106
	v_cmp_lt_i32_e64 s[0:1], v138, v107
	s_and_b64 s[16:17], vcc, s[0:1]
	s_and_saveexec_b64 s[0:1], s[16:17]
	v_add_co_u32_e32 v136, vcc, 0x10e06000, v140
	s_nop 1
	v_addc_co_u32_e32 v137, vcc, 0, v141, vcc
	global_load_dwordx4 v[120:123], v[136:137], off offset:1536
	s_mov_b64 exec, s[0:1]
	v_add_u32_e32 v138, 3, v108
	v_cmp_ge_i32_e32 vcc, v138, v106
	v_cmp_lt_i32_e64 s[0:1], v138, v107
	s_and_b64 s[16:17], vcc, s[0:1]
	s_and_saveexec_b64 s[0:1], s[16:17]
	v_add_co_u32_e32 v136, vcc, 0x10e09000, v140
	s_nop 1
	v_addc_co_u32_e32 v137, vcc, 0, v141, vcc
	global_load_dwordx4 v[124:127], v[136:137], off offset:512
	s_mov_b64 exec, s[0:1]
	v_add_u32_e32 v138, 4, v108
	v_cmp_ge_i32_e32 vcc, v138, v106
	v_cmp_lt_i32_e64 s[0:1], v138, v107
	s_and_b64 s[16:17], vcc, s[0:1]
	s_and_saveexec_b64 s[0:1], s[16:17]
	v_mad_i64_i32 v[136:137], s[16:17], v138, s45, v[72:73]
	global_load_dwordx4 v[128:131], v[136:137], off
	s_mov_b64 exec, s[0:1]
	v_add_u32_e32 v138, 5, v108
	v_cmp_ge_i32_e32 vcc, v138, v106
	v_cmp_lt_i32_e64 s[0:1], v138, v107
	s_and_b64 s[16:17], vcc, s[0:1]
	s_and_saveexec_b64 s[0:1], s[16:17]
	v_mad_i64_i32 v[136:137], s[16:17], v138, s45, v[72:73]
	global_load_dwordx4 v[132:135], v[136:137], off
	s_mov_b64 exec, s[0:1]
	s_waitcnt vmcnt(0)
	s_mov_b32 s10, 0
	s_branch .LBB0_130
.LBB0_129:
	s_or_b64 exec, exec, s[0:1]
	v_add_u32_e32 v138, 4, v109
	v_cmp_ge_i32_e32 vcc, v138, v106
	v_cmp_lt_i32_e64 s[0:1], v138, v107
	s_and_b64 s[16:17], vcc, s[0:1]
	s_and_saveexec_b64 s[0:1], s[16:17]
	v_mad_i64_i32 v[136:137], s[16:17], v138, s45, v[72:73]
	global_load_dwordx4 v[132:135], v[136:137], off
	s_mov_b64 exec, s[0:1]
	v_pk_fma_f32 v[68:69], v[4:5], v[68:69], v[44:45]
	v_pk_fma_f32 v[64:65], v[6:7], v[64:65], v[46:47]
	v_pk_fma_f32 v[68:69], v[8:9], v[78:79], v[68:69]
	v_pk_fma_f32 v[82:83], v[0:1], v[82:83], v[40:41]
	v_pk_fma_f32 v[66:67], v[2:3], v[66:67], v[42:43]
	v_pk_fma_f32 v[68:69], v[16:17], v[98:99], v[68:69]
	v_pk_fma_f32 v[64:65], v[10:11], v[80:81], v[64:65]
	v_pk_fma_f32 v[82:83], v[12:13], v[84:85], v[82:83]
	v_pk_fma_f32 v[66:67], v[14:15], v[86:87], v[66:67]
	v_pk_fma_f32 v[68:69], v[24:25], v[90:91], v[68:69]
	v_lshlrev_b32_e32 v78, 16, v56
	v_and_b32_e32 v79, 0xffff0000, v56
	v_pk_fma_f32 v[64:65], v[18:19], v[100:101], v[64:65]
	v_pk_fma_f32 v[82:83], v[20:21], v[102:103], v[82:83]
	v_pk_fma_f32 v[66:67], v[22:23], v[104:105], v[66:67]
	v_pk_fma_f32 v[68:69], v[32:33], v[78:79], v[68:69]
	v_pk_fma_f32 v[64:65], v[26:27], v[92:93], v[64:65]
	v_lshlrev_b32_e32 v80, 16, v57
	v_and_b32_e32 v81, 0xffff0000, v57
	v_pk_fma_f32 v[82:83], v[28:29], v[94:95], v[82:83]
	v_lshlrev_b32_e32 v84, 16, v58
	v_and_b32_e32 v85, 0xffff0000, v58
	v_pk_fma_f32 v[66:67], v[30:31], v[96:97], v[66:67]
	v_lshlrev_b32_e32 v86, 16, v59
	v_and_b32_e32 v87, 0xffff0000, v59
	v_mul_f32_e32 v78, 0xbfb8aa3b, v68
	v_mul_f32_e32 v79, 0xbfb8aa3b, v69
	v_pk_fma_f32 v[64:65], v[34:35], v[80:81], v[64:65]
	v_pk_fma_f32 v[82:83], v[36:37], v[84:85], v[82:83]
	v_pk_fma_f32 v[66:67], v[38:39], v[86:87], v[66:67]
	v_exp_f32_e32 v78, v78
	v_exp_f32_e32 v79, v79
	v_mul_f32_e32 v80, 0xbfb8aa3b, v64
	v_mul_f32_e32 v81, 0xbfb8aa3b, v65
	v_mul_f32_e32 v84, 0xbfb8aa3b, v82
	v_mul_f32_e32 v85, 0xbfb8aa3b, v83
	v_mul_f32_e32 v86, 0xbfb8aa3b, v66
	v_mul_f32_e32 v87, 0xbfb8aa3b, v67
	v_exp_f32_e32 v80, v80
	v_exp_f32_e32 v81, v81
	v_exp_f32_e32 v84, v84
	v_exp_f32_e32 v85, v85
	v_exp_f32_e32 v86, v86
	v_exp_f32_e32 v87, v87
	v_add_f32_e32 v78, 1.0, v78
	v_add_f32_e32 v79, 1.0, v79
	v_rcp_f32_e32 v78, v78
	v_rcp_f32_e32 v79, v79
	v_add_f32_e32 v80, 1.0, v80
	v_add_f32_e32 v81, 1.0, v81
	v_add_f32_e32 v84, 1.0, v84
	v_add_f32_e32 v85, 1.0, v85
	v_add_f32_e32 v86, 1.0, v86
	v_add_f32_e32 v87, 1.0, v87
	v_rcp_f32_e32 v80, v80
	v_rcp_f32_e32 v81, v81
	v_rcp_f32_e32 v84, v84
	v_rcp_f32_e32 v85, v85
	v_rcp_f32_e32 v86, v86
	v_rcp_f32_e32 v87, v87
	v_pk_mul_f32 v[68:69], v[68:69], v[78:79]
	v_pk_mul_f32 v[78:79], v[64:65], v[80:81]
	v_pk_mul_f32 v[80:81], v[82:83], v[84:85]
	v_pk_mul_f32 v[82:83], v[66:67], v[86:87]
	v_cvt_pk_bf16_f32 v64, v68, v69
	v_add_co_u32_e32 v68, vcc, 0x38e01000, v88
	v_cvt_pk_bf16_f32 v65, v78, v79
	v_cvt_pk_bf16_f32 v66, v80, v81
	v_cvt_pk_bf16_f32 v67, v82, v83
	v_addc_co_u32_e32 v69, vcc, 0, v89, vcc
	s_add_i32 s10, s10, 4
	s_mov_b64 s[0:1], 0xb000
	global_store_dwordx4 v[68:69], v[64:67], off offset:3584
	v_lshl_add_u64 v[74:75], v[74:75], 0, s[52:53]
	v_lshl_add_u64 v[76:77], v[76:77], 0, s[0:1]
	s_cmp_lg_u32 s10, 32
	v_mov_b32_e32 v68, v48
	v_mov_b32_e32 v64, v52
	v_mov_b32_e32 v65, v53
	v_mov_b32_e32 v66, v54
	v_mov_b32_e32 v67, v55
	s_cbranch_scc0 .LBB0_118
.LBB0_130:
	v_add_u32_e32 v109, s10, v108
	v_add_u32_e32 v48, 2, v109
	v_cmp_ge_i32_e32 vcc, v48, v106
	v_cmp_lt_i32_e64 s[0:1], v48, v107
	s_and_b64 s[16:17], vcc, s[0:1]
	v_mov_b32_e32 v48, 0
	v_lshl_add_u64 v[98:99], v[76:77], 0, v[70:71]
	v_mov_b32_e32 v52, 0
	v_mov_b32_e32 v53, 0
	v_mov_b32_e32 v54, 0
	v_mov_b32_e32 v55, 0
	s_and_saveexec_b64 s[0:1], s[16:17]
	s_cbranch_execz .LBB0_132
	s_waitcnt vmcnt(7)
	v_mov_b32_e32 v52, v120
	v_mov_b32_e32 v53, v121
	v_mov_b32_e32 v54, v122
	v_mov_b32_e32 v55, v123
; __device__ __forceinline__ unsigned cvtpk(float lo, float hi) { f32x2 v = {lo, hi}; bf16x2_t b = __builtin_convertvector(v, bf16x2_t); return __builtin_bit_cast(unsigned, b); }
; __device__ __forceinline__ float siluf_(float x) { return x * __builtin_amdgcn_rcpf(1.f + __builtin_amdgcn_exp2f(x * -LOG2E)); }
; __device__ __forceinline__ void xbc_conv_item(CP& P, int L, int item) {
;     ...
;     for (int j = 0; j < 4; ++j) { const int t = r0 - 2 + j; win[j + 1] = (t >= s0 && t < s1) ? *(const u32x4*)(src + (size_t)t * PROJ_PITCH) : (u32x4){0u, 0u, 0u, 0u}; }
; #pragma unroll 4
;     for (int r = 0; r < 32; ++r) {
; #pragma unroll
;         for (int j = 0; j < 4; ++j) win[j] = win[j + 1];
;         { const int t = r0 + r + 2; win[4] = (t >= s0 && t < s1) ? *(const u32x4*)(src + (size_t)t * PROJ_PITCH) : (u32x4){0u, 0u, 0u, 0u}; }
;         float a[8];
; #pragma unroll
;         for (int k = 0; k < 8; ++k) a[k] = bs[k];
; #pragma unroll
;         for (int j = 0; j < 5; ++j) { float x[8]; unpack8(win[j], x);
; #pragma unroll
;             for (int k = 0; k < 8; ++k) a[k] += x[k] * w[j][k]; }
; #pragma unroll
;         for (int k = 0; k < 8; ++k) a[k] = siluf_(a[k]);
;         u32x4 o; o.x = cvtpk(a[0], a[1]); o.y = cvtpk(a[2], a[3]); o.z = cvtpk(a[4], a[5]); o.w = cvtpk(a[6], a[7]);
;         *(u32x4*)(xbc + (size_t)(r0 + r) * XBC_W + c8) = o;
;     }
.LBB0_132:
	s_or_b64 exec, exec, s[0:1]
	v_add_u32_e32 v138, 6, v109
	v_cmp_ge_i32_e32 vcc, v138, v106
	v_cmp_lt_i32_e64 s[0:1], v138, v107
	s_and_b64 s[16:17], vcc, s[0:1]
	s_and_saveexec_b64 s[0:1], s[16:17]
	v_add_co_u32_e32 v136, vcc, 0x10e11000, v98
	s_nop 1
	v_addc_co_u32_e32 v137, vcc, 0, v99, vcc
	global_load_dwordx4 v[120:123], v[136:137], off offset:1536
	s_mov_b64 exec, s[0:1]
	v_lshlrev_b32_e32 v78, 16, v64
	v_and_b32_e32 v79, 0xffff0000, v64
	v_pk_fma_f32 v[78:79], v[4:5], v[78:79], v[44:45]
	v_lshlrev_b32_e32 v100, 16, v68
	v_and_b32_e32 v101, 0xffff0000, v68
	v_pk_fma_f32 v[68:69], v[8:9], v[100:101], v[78:79]
	v_lshlrev_b32_e32 v90, 16, v60
	v_and_b32_e32 v91, 0xffff0000, v60
	v_pk_fma_f32 v[78:79], v[16:17], v[90:91], v[68:69]
	v_lshlrev_b32_e32 v68, 16, v56
	v_and_b32_e32 v69, 0xffff0000, v56
	v_pk_fma_f32 v[80:81], v[24:25], v[68:69], v[78:79]
	v_lshlrev_b32_e32 v78, 16, v52
	v_and_b32_e32 v79, 0xffff0000, v52
	v_pk_fma_f32 v[80:81], v[32:33], v[78:79], v[80:81]
	v_lshlrev_b32_e32 v64, 16, v65
	v_mul_f32_e32 v56, 0xbfb8aa3b, v80
	v_exp_f32_e32 v56, v56
	v_and_b32_e32 v65, 0xffff0000, v65
	v_pk_fma_f32 v[64:65], v[6:7], v[64:65], v[46:47]
	v_lshlrev_b32_e32 v102, 16, v49
	v_add_f32_e32 v56, 1.0, v56
	v_rcp_f32_e32 v82, v56
	v_mul_f32_e32 v56, 0xbfb8aa3b, v81
	v_exp_f32_e32 v56, v56
	v_and_b32_e32 v103, 0xffff0000, v49
	v_pk_fma_f32 v[64:65], v[10:11], v[102:103], v[64:65]
	v_lshlrev_b32_e32 v92, 16, v61
	v_add_f32_e32 v56, 1.0, v56
	v_rcp_f32_e32 v83, v56
	v_and_b32_e32 v93, 0xffff0000, v61
	v_pk_fma_f32 v[60:61], v[18:19], v[92:93], v[64:65]
	v_lshlrev_b32_e32 v64, 16, v57
	v_and_b32_e32 v65, 0xffff0000, v57
	v_pk_mul_f32 v[88:89], v[80:81], v[82:83]
	v_pk_fma_f32 v[56:57], v[26:27], v[64:65], v[60:61]
	v_lshlrev_b32_e32 v80, 16, v53
	v_and_b32_e32 v81, 0xffff0000, v53
	v_pk_fma_f32 v[56:57], v[34:35], v[80:81], v[56:57]
	v_lshlrev_b32_e32 v94, 16, v62
	v_mul_f32_e32 v49, 0xbfb8aa3b, v56
	v_exp_f32_e32 v49, v49
	v_and_b32_e32 v95, 0xffff0000, v62
	v_lshlrev_b32_e32 v82, 16, v58
	v_and_b32_e32 v83, 0xffff0000, v58
	v_add_f32_e32 v49, 1.0, v49
	v_rcp_f32_e32 v60, v49
	v_mul_f32_e32 v49, 0xbfb8aa3b, v57
	v_exp_f32_e32 v49, v49
	v_lshlrev_b32_e32 v84, 16, v54
	v_and_b32_e32 v85, 0xffff0000, v54
	v_lshlrev_b32_e32 v96, 16, v63
	v_add_f32_e32 v49, 1.0, v49
	v_rcp_f32_e32 v61, v49
	v_and_b32_e32 v97, 0xffff0000, v63
	v_cvt_pk_bf16_f32 v110, v88, v89
	v_lshl_add_u64 v[88:89], v[74:75], 0, v[70:71]
	v_pk_mul_f32 v[104:105], v[56:57], v[60:61]
	v_lshlrev_b32_e32 v56, 16, v66
	v_and_b32_e32 v57, 0xffff0000, v66
	v_pk_fma_f32 v[60:61], v[0:1], v[56:57], v[40:41]
	v_lshlrev_b32_e32 v56, 16, v50
	v_and_b32_e32 v57, 0xffff0000, v50
	v_pk_fma_f32 v[60:61], v[12:13], v[56:57], v[60:61]
	v_cvt_pk_bf16_f32 v111, v104, v105
	v_pk_fma_f32 v[60:61], v[20:21], v[94:95], v[60:61]
	s_nop 0
	v_pk_fma_f32 v[60:61], v[28:29], v[82:83], v[60:61]
	s_nop 0
	v_pk_fma_f32 v[60:61], v[36:37], v[84:85], v[60:61]
	s_nop 0
	v_mul_f32_e32 v49, 0xbfb8aa3b, v60
	v_exp_f32_e32 v49, v49
	s_nop 0
	v_add_f32_e32 v49, 1.0, v49
	v_rcp_f32_e32 v86, v49
	v_mul_f32_e32 v49, 0xbfb8aa3b, v61
	v_exp_f32_e32 v49, v49
	s_nop 0
	v_add_f32_e32 v49, 1.0, v49
	v_rcp_f32_e32 v87, v49
	s_nop 0
	v_pk_mul_f32 v[112:113], v[60:61], v[86:87]
	v_lshlrev_b32_e32 v60, 16, v67
	v_and_b32_e32 v61, 0xffff0000, v67
	v_pk_fma_f32 v[66:67], v[2:3], v[60:61], v[42:43]
	v_lshlrev_b32_e32 v60, 16, v51
	v_and_b32_e32 v61, 0xffff0000, v51
	v_pk_fma_f32 v[50:51], v[14:15], v[60:61], v[66:67]
	v_lshlrev_b32_e32 v66, 16, v59
	v_pk_fma_f32 v[50:51], v[22:23], v[96:97], v[50:51]
	v_and_b32_e32 v67, 0xffff0000, v59
	v_pk_fma_f32 v[50:51], v[30:31], v[66:67], v[50:51]
	v_lshlrev_b32_e32 v86, 16, v55
	v_and_b32_e32 v87, 0xffff0000, v55
	v_pk_fma_f32 v[50:51], v[38:39], v[86:87], v[50:51]
	v_cvt_pk_bf16_f32 v112, v112, v113
	v_mul_f32_e32 v49, 0xbfb8aa3b, v50
	v_exp_f32_e32 v49, v49
	s_nop 0
	v_add_f32_e32 v49, 1.0, v49
	v_rcp_f32_e32 v58, v49
	v_mul_f32_e32 v49, 0xbfb8aa3b, v51
	v_exp_f32_e32 v49, v49
	s_nop 0
	v_add_f32_e32 v49, 1.0, v49
	v_rcp_f32_e32 v59, v49
	v_add_u32_e32 v49, 3, v109
	v_cmp_lt_i32_e64 s[0:1], v49, v107
	v_pk_mul_f32 v[50:51], v[50:51], v[58:59]
	s_nop 0
	v_cvt_pk_bf16_f32 v113, v50, v51
	v_add_co_u32_e32 v50, vcc, 0x38e00000, v88
	s_nop 1
	v_addc_co_u32_e32 v51, vcc, 0, v89, vcc
	v_cmp_ge_i32_e32 vcc, v49, v106
	global_store_dwordx4 v[50:51], v[110:113], off
	s_and_b64 s[16:17], vcc, s[0:1]
	v_mov_b32_e32 v49, 0
	v_mov_b32_e32 v50, 0
	v_mov_b32_e32 v51, 0
	s_and_saveexec_b64 s[0:1], s[16:17]
	s_cbranch_execz .LBB0_134
	s_waitcnt vmcnt(7)
	v_mov_b32_e32 v48, v124
	v_mov_b32_e32 v49, v125
	v_mov_b32_e32 v50, v126
	v_mov_b32_e32 v51, v127
; __device__ __forceinline__ unsigned cvtpk(float lo, float hi) { f32x2 v = {lo, hi}; bf16x2_t b = __builtin_convertvector(v, bf16x2_t); return __builtin_bit_cast(unsigned, b); }
; __device__ __forceinline__ float siluf_(float x) { return x * __builtin_amdgcn_rcpf(1.f + __builtin_amdgcn_exp2f(x * -LOG2E)); }
; __device__ __forceinline__ void xbc_conv_item(CP& P, int L, int item) {
;     ...
;     for (int j = 0; j < 4; ++j) { const int t = r0 - 2 + j; win[j + 1] = (t >= s0 && t < s1) ? *(const u32x4*)(src + (size_t)t * PROJ_PITCH) : (u32x4){0u, 0u, 0u, 0u}; }
; #pragma unroll 4
;     for (int r = 0; r < 32; ++r) {
; #pragma unroll
;         for (int j = 0; j < 4; ++j) win[j] = win[j + 1];
;         { const int t = r0 + r + 2; win[4] = (t >= s0 && t < s1) ? *(const u32x4*)(src + (size_t)t * PROJ_PITCH) : (u32x4){0u, 0u, 0u, 0u}; }
;         float a[8];
; #pragma unroll
;         for (int k = 0; k < 8; ++k) a[k] = bs[k];
; #pragma unroll
;         for (int j = 0; j < 5; ++j) { float x[8]; unpack8(win[j], x);
; #pragma unroll
;             for (int k = 0; k < 8; ++k) a[k] += x[k] * w[j][k]; }
; #pragma unroll
;         for (int k = 0; k < 8; ++k) a[k] = siluf_(a[k]);
;         u32x4 o; o.x = cvtpk(a[0], a[1]); o.y = cvtpk(a[2], a[3]); o.z = cvtpk(a[4], a[5]); o.w = cvtpk(a[6], a[7]);
;         *(u32x4*)(xbc + (size_t)(r0 + r) * XBC_W + c8) = o;
;     }
.LBB0_134:
	s_or_b64 exec, exec, s[0:1]
	v_add_u32_e32 v138, 7, v109
	v_cmp_ge_i32_e32 vcc, v138, v106
	v_cmp_lt_i32_e64 s[0:1], v138, v107
	s_and_b64 s[16:17], vcc, s[0:1]
	s_and_saveexec_b64 s[0:1], s[16:17]
	v_add_co_u32_e32 v136, vcc, 0x10e14000, v98
	s_nop 1
	v_addc_co_u32_e32 v137, vcc, 0, v99, vcc
	global_load_dwordx4 v[124:127], v[136:137], off offset:512
	s_mov_b64 exec, s[0:1]
	v_pk_fma_f32 v[58:59], v[4:5], v[100:101], v[44:45]
	v_lshlrev_b32_e32 v98, 16, v48
	v_pk_fma_f32 v[58:59], v[8:9], v[90:91], v[58:59]
	v_and_b32_e32 v99, 0xffff0000, v48
	v_pk_fma_f32 v[58:59], v[16:17], v[68:69], v[58:59]
	v_lshlrev_b32_e32 v100, 16, v49
	v_pk_fma_f32 v[58:59], v[24:25], v[78:79], v[58:59]
	v_and_b32_e32 v101, 0xffff0000, v49
	v_pk_fma_f32 v[58:59], v[32:33], v[98:99], v[58:59]
	v_pk_fma_f32 v[56:57], v[0:1], v[56:57], v[40:41]
	v_mul_f32_e32 v62, 0xbfb8aa3b, v58
	v_mul_f32_e32 v63, 0xbfb8aa3b, v59
	v_exp_f32_e32 v62, v62
	v_exp_f32_e32 v63, v63
	v_pk_fma_f32 v[56:57], v[12:13], v[94:95], v[56:57]
	v_add_f32_e32 v62, 1.0, v62
	v_add_f32_e32 v63, 1.0, v63
	v_rcp_f32_e32 v62, v62
	v_rcp_f32_e32 v63, v63
	v_pk_fma_f32 v[56:57], v[20:21], v[82:83], v[56:57]
	v_pk_mul_f32 v[58:59], v[58:59], v[62:63]
	v_pk_fma_f32 v[62:63], v[6:7], v[102:103], v[46:47]
	v_pk_fma_f32 v[56:57], v[28:29], v[84:85], v[56:57]
	v_pk_fma_f32 v[62:63], v[10:11], v[92:93], v[62:63]
	s_nop 0
	v_pk_fma_f32 v[62:63], v[18:19], v[64:65], v[62:63]
	s_nop 0
	v_pk_fma_f32 v[62:63], v[26:27], v[80:81], v[62:63]
	s_nop 0
	v_pk_fma_f32 v[62:63], v[34:35], v[100:101], v[62:63]
	s_nop 0
	v_mul_f32_e32 v102, 0xbfb8aa3b, v62
	v_mul_f32_e32 v103, 0xbfb8aa3b, v63
	v_exp_f32_e32 v102, v102
	v_exp_f32_e32 v103, v103
	v_add_f32_e32 v102, 1.0, v102
	v_add_f32_e32 v103, 1.0, v103
	v_rcp_f32_e32 v102, v102
	v_rcp_f32_e32 v103, v103
	s_nop 0
	v_pk_mul_f32 v[62:63], v[62:63], v[102:103]
	v_lshlrev_b32_e32 v102, 16, v50
	v_and_b32_e32 v103, 0xffff0000, v50
	v_pk_fma_f32 v[56:57], v[36:37], v[102:103], v[56:57]
	s_nop 0
	v_mul_f32_e32 v104, 0xbfb8aa3b, v56
	v_mul_f32_e32 v105, 0xbfb8aa3b, v57
	v_exp_f32_e32 v104, v104
	v_exp_f32_e32 v105, v105
	v_add_f32_e32 v104, 1.0, v104
	v_add_f32_e32 v105, 1.0, v105
	v_rcp_f32_e32 v104, v104
	v_rcp_f32_e32 v105, v105
	s_nop 0
	v_pk_mul_f32 v[110:111], v[56:57], v[104:105]
	v_pk_fma_f32 v[56:57], v[2:3], v[60:61], v[42:43]
	v_lshlrev_b32_e32 v104, 16, v51
	v_pk_fma_f32 v[56:57], v[14:15], v[96:97], v[56:57]
	v_and_b32_e32 v105, 0xffff0000, v51
	v_pk_fma_f32 v[56:57], v[22:23], v[66:67], v[56:57]
	s_nop 0
	v_pk_fma_f32 v[56:57], v[30:31], v[86:87], v[56:57]
	s_nop 0
	v_pk_fma_f32 v[56:57], v[38:39], v[104:105], v[56:57]
	s_nop 0
	v_mul_f32_e32 v60, 0xbfb8aa3b, v56
	v_mul_f32_e32 v61, 0xbfb8aa3b, v57
	v_exp_f32_e32 v60, v60
	v_exp_f32_e32 v61, v61
	v_add_f32_e32 v60, 1.0, v60
	v_add_f32_e32 v61, 1.0, v61
	v_rcp_f32_e32 v60, v60
	v_rcp_f32_e32 v61, v61
	s_nop 0
	v_pk_mul_f32 v[60:61], v[56:57], v[60:61]
	v_cvt_pk_bf16_f32 v56, v58, v59
	v_cvt_pk_bf16_f32 v59, v60, v61
	v_add_co_u32_e32 v60, vcc, 0x38e00000, v88
	v_cvt_pk_bf16_f32 v57, v62, v63
	v_cvt_pk_bf16_f32 v58, v110, v111
	v_addc_co_u32_e32 v61, vcc, 0, v89, vcc
	global_store_dwordx4 v[60:61], v[56:59], off offset:2560
	v_mov_b32_e32 v60, 0
	v_mov_b32_e32 v61, 0
	v_add_u32_e32 v57, 4, v109
	v_cmp_ge_i32_e32 vcc, v57, v106
	v_cmp_lt_i32_e64 s[0:1], v57, v107
	s_and_b64 s[16:17], vcc, s[0:1]
	v_mov_b32_e32 v56, 0
	v_mov_b32_e32 v62, 0
	v_mov_b32_e32 v63, 0
	s_and_saveexec_b64 s[0:1], s[16:17]
	s_cbranch_execz .LBB0_136
	s_waitcnt vmcnt(7)
	v_mov_b32_e32 v60, v128
	v_mov_b32_e32 v61, v129
	v_mov_b32_e32 v62, v130
	v_mov_b32_e32 v63, v131
; __device__ __forceinline__ unsigned cvtpk(float lo, float hi) { f32x2 v = {lo, hi}; bf16x2_t b = __builtin_convertvector(v, bf16x2_t); return __builtin_bit_cast(unsigned, b); }
; __device__ __forceinline__ float siluf_(float x) { return x * __builtin_amdgcn_rcpf(1.f + __builtin_amdgcn_exp2f(x * -LOG2E)); }
; __device__ __forceinline__ void xbc_conv_item(CP& P, int L, int item) {
;     ...
;     for (int j = 0; j < 4; ++j) { const int t = r0 - 2 + j; win[j + 1] = (t >= s0 && t < s1) ? *(const u32x4*)(src + (size_t)t * PROJ_PITCH) : (u32x4){0u, 0u, 0u, 0u}; }
; #pragma unroll 4
;     for (int r = 0; r < 32; ++r) {
; #pragma unroll
;         for (int j = 0; j < 4; ++j) win[j] = win[j + 1];
;         { const int t = r0 + r + 2; win[4] = (t >= s0 && t < s1) ? *(const u32x4*)(src + (size_t)t * PROJ_PITCH) : (u32x4){0u, 0u, 0u, 0u}; }
;         float a[8];
; #pragma unroll
;         for (int k = 0; k < 8; ++k) a[k] = bs[k];
; #pragma unroll
;         for (int j = 0; j < 5; ++j) { float x[8]; unpack8(win[j], x);
; #pragma unroll
;             for (int k = 0; k < 8; ++k) a[k] += x[k] * w[j][k]; }
; #pragma unroll
;         for (int k = 0; k < 8; ++k) a[k] = siluf_(a[k]);
;         u32x4 o; o.x = cvtpk(a[0], a[1]); o.y = cvtpk(a[2], a[3]); o.z = cvtpk(a[4], a[5]); o.w = cvtpk(a[6], a[7]);
;         *(u32x4*)(xbc + (size_t)(r0 + r) * XBC_W + c8) = o;
;     }
.LBB0_136:
	s_or_b64 exec, exec, s[0:1]
	v_add_u32_e32 v138, 8, v109
	v_cmp_ge_i32_e32 vcc, v138, v106
	v_cmp_lt_i32_e64 s[0:1], v138, v107
	s_and_b64 s[16:17], vcc, s[0:1]
	s_and_saveexec_b64 s[0:1], s[16:17]
	v_mad_i64_i32 v[136:137], s[16:17], v138, s45, v[72:73]
	global_load_dwordx4 v[128:131], v[136:137], off
	s_mov_b64 exec, s[0:1]
	v_pk_fma_f32 v[58:59], v[4:5], v[90:91], v[44:45]
	v_lshlrev_b32_e32 v90, 16, v60
	v_pk_fma_f32 v[58:59], v[8:9], v[68:69], v[58:59]
	v_and_b32_e32 v91, 0xffff0000, v60
	v_pk_fma_f32 v[58:59], v[16:17], v[78:79], v[58:59]
	v_pk_fma_f32 v[92:93], v[6:7], v[92:93], v[46:47]
	v_pk_fma_f32 v[58:59], v[24:25], v[98:99], v[58:59]
	v_pk_fma_f32 v[92:93], v[10:11], v[64:65], v[92:93]
	v_pk_fma_f32 v[58:59], v[32:33], v[90:91], v[58:59]
	v_pk_fma_f32 v[92:93], v[18:19], v[80:81], v[92:93]
	v_mul_f32_e32 v57, 0xbfb8aa3b, v58
	v_exp_f32_e32 v57, v57
	v_pk_fma_f32 v[94:95], v[0:1], v[94:95], v[40:41]
	v_pk_fma_f32 v[96:97], v[2:3], v[96:97], v[42:43]
	v_pk_fma_f32 v[94:95], v[12:13], v[82:83], v[94:95]
	v_add_f32_e32 v57, 1.0, v57
	v_rcp_f32_e32 v110, v57
	v_mul_f32_e32 v57, 0xbfb8aa3b, v59
	v_exp_f32_e32 v57, v57
	v_pk_fma_f32 v[94:95], v[20:21], v[84:85], v[94:95]
	v_pk_fma_f32 v[96:97], v[14:15], v[66:67], v[96:97]
	v_add_u32_e32 v109, 5, v109
	v_add_f32_e32 v57, 1.0, v57
	v_rcp_f32_e32 v111, v57
	v_pk_fma_f32 v[96:97], v[22:23], v[86:87], v[96:97]
	v_cmp_lt_i32_e64 s[0:1], v109, v107
	v_pk_mul_f32 v[58:59], v[58:59], v[110:111]
	v_pk_fma_f32 v[110:111], v[26:27], v[100:101], v[92:93]
	v_lshlrev_b32_e32 v92, 16, v61
	v_and_b32_e32 v93, 0xffff0000, v61
	v_pk_fma_f32 v[110:111], v[34:35], v[92:93], v[110:111]
	s_nop 0
	v_mul_f32_e32 v57, 0xbfb8aa3b, v110
	v_exp_f32_e32 v57, v57
	s_nop 0
	v_add_f32_e32 v57, 1.0, v57
	v_rcp_f32_e32 v112, v57
	v_mul_f32_e32 v57, 0xbfb8aa3b, v111
	v_exp_f32_e32 v57, v57
	s_nop 0
	v_add_f32_e32 v57, 1.0, v57
	v_rcp_f32_e32 v113, v57
	s_nop 0
	v_pk_mul_f32 v[112:113], v[110:111], v[112:113]
	v_pk_fma_f32 v[110:111], v[28:29], v[102:103], v[94:95]
	v_lshlrev_b32_e32 v94, 16, v62
	v_and_b32_e32 v95, 0xffff0000, v62
	v_pk_fma_f32 v[110:111], v[36:37], v[94:95], v[110:111]
	s_nop 0
	v_mul_f32_e32 v57, 0xbfb8aa3b, v110
	v_exp_f32_e32 v57, v57
	s_nop 0
	v_add_f32_e32 v57, 1.0, v57
	v_rcp_f32_e32 v114, v57
	v_mul_f32_e32 v57, 0xbfb8aa3b, v111
	v_exp_f32_e32 v57, v57
	s_nop 0
	v_add_f32_e32 v57, 1.0, v57
	v_rcp_f32_e32 v115, v57
	s_nop 0
	v_pk_mul_f32 v[114:115], v[110:111], v[114:115]
	v_pk_fma_f32 v[110:111], v[30:31], v[104:105], v[96:97]
	v_lshlrev_b32_e32 v96, 16, v63
	v_and_b32_e32 v97, 0xffff0000, v63
	v_pk_fma_f32 v[110:111], v[38:39], v[96:97], v[110:111]
	s_nop 0
	v_mul_f32_e32 v57, 0xbfb8aa3b, v110
	v_exp_f32_e32 v57, v57
	s_nop 0
	v_add_f32_e32 v57, 1.0, v57
	v_rcp_f32_e32 v116, v57
	v_mul_f32_e32 v57, 0xbfb8aa3b, v111
	v_exp_f32_e32 v57, v57
	s_nop 0
	v_add_f32_e32 v57, 1.0, v57
	v_rcp_f32_e32 v117, v57
	v_mov_b32_e32 v57, 0
	v_pk_mul_f32 v[116:117], v[110:111], v[116:117]
	v_cvt_pk_bf16_f32 v110, v58, v59
	v_add_co_u32_e32 v58, vcc, 0x38e01000, v88
	v_cvt_pk_bf16_f32 v111, v112, v113
	s_nop 0
	v_addc_co_u32_e32 v59, vcc, 0, v89, vcc
	v_cvt_pk_bf16_f32 v112, v114, v115
	v_cvt_pk_bf16_f32 v113, v116, v117
	v_cmp_ge_i32_e32 vcc, v109, v106
	global_store_dwordx4 v[58:59], v[110:113], off offset:1024
	s_and_b64 s[16:17], vcc, s[0:1]
	v_mov_b32_e32 v58, 0
	v_mov_b32_e32 v59, 0
	s_and_saveexec_b64 s[0:1], s[16:17]
	s_cbranch_execz .LBB0_129
	s_waitcnt vmcnt(7)
	v_mov_b32_e32 v56, v132
	v_mov_b32_e32 v57, v133
	v_mov_b32_e32 v58, v134
	v_mov_b32_e32 v59, v135
	s_branch .LBB0_129

; __device__ __forceinline__ unsigned cvtpk(float lo, float hi) { f32x2 v = {lo, hi}; bf16x2_t b = __builtin_convertvector(v, bf16x2_t); return __builtin_bit_cast(unsigned, b); }
; __global__ void __launch_bounds__(512, 2) hybrid_fwd(Params P0) {
;     ...
;             if (sub == 7) {
;                 bf16_t* PB = (bf16_t*)(P.ws + WS_PB);
;                 for (int m = gw; m < T; m += NGW) {
;                     const float* pr = (m < TP) ? P.in[I_PP] + ((size_t)L * TP + m) * PLE : P.in[I_PS] + ((size_t)L * TS + (m - TP)) * PLE;
;                     const f32x4 v = *((const f32x4*)pr + lane); u32x2 w; w.x = cvtpk(v.x, v.y); w.y = cvtpk(v.z, v.w); *((u32x2*)(PB + (size_t)m * PLE) + lane) = w; }
;             }
.LBB0_176:
	s_and_b64 vcc, exec, s[16:17]
	s_cbranch_vccz .LBB0_398
	s_cmp_lg_u32 s57, 7
	s_cselect_b64 s[0:1], -1, 0
	s_cmp_eq_u32 s57, 7
	s_cselect_b64 s[4:5], -1, 0
	s_cmp_lt_i32 s68, 0xa000
	s_cselect_b64 s[6:7], -1, 0
	s_and_b64 s[4:5], s[4:5], s[6:7]
	s_andn2_b64 vcc, exec, s[4:5]
	s_cbranch_vccnz .LBB0_184
	v_lshlrev_b32_e32 v192, 3, v198
	s_ashr_i32 s29, s28, 31
	v_lshl_add_u64 v[0:1], s[26:27], 0, v[192:193]
	s_mov_b64 s[8:9], 0x38e00000
	s_ashr_i32 s69, s68, 31
	v_lshl_add_u64 v[0:1], v[0:1], 0, s[8:9]
	v_lshlrev_b32_e32 v2, 4, v198
	s_load_dwordx2 s[18:19], s[64:65], 0x10
	s_load_dwordx2 s[20:21], s[64:65], 0x18
	s_lshl_b64 s[4:5], s[28:29], 25
	s_lshl_b64 s[6:7], s[28:29], 23
	s_waitcnt lgkmcnt(0)
	s_add_u32 s18, s18, s6
	s_addc_u32 s19, s19, s7
	s_add_u32 s20, s20, s4
	s_addc_u32 s21, s21, s5
	s_sub_u32 s20, s20, 0x800000
	s_subb_u32 s21, s21, 0
	s_mov_b32 s6, s68
	s_mov_b32 s11, 0
.Lpb_batch:
	s_mov_b32 s14, s6
	s_cmp_ge_i32 s14, 0xa000
	s_cbranch_scc1 .Lpb_ld_done
	s_cmpk_gt_i32 s14, 0x1fff
	s_cselect_b32 s8, s20, s18
	s_cselect_b32 s9, s21, s19
	s_lshl_b32 s10, s14, 10
	s_add_u32 s8, s8, s10
	s_addc_u32 s9, s9, 0
	global_load_dwordx4 v[4:7], v2, s[8:9]
	s_add_i32 s14, s14, s86
	s_cmp_ge_i32 s14, 0xa000
	s_cbranch_scc1 .Lpb_ld_done
	s_cmpk_gt_i32 s14, 0x1fff
	s_cselect_b32 s8, s20, s18
	s_cselect_b32 s9, s21, s19
	s_lshl_b32 s10, s14, 10
	s_add_u32 s8, s8, s10
	s_addc_u32 s9, s9, 0
	global_load_dwordx4 v[8:11], v2, s[8:9]
	s_add_i32 s14, s14, s86
	s_cmp_ge_i32 s14, 0xa000
	s_cbranch_scc1 .Lpb_ld_done
	s_cmpk_gt_i32 s14, 0x1fff
	s_cselect_b32 s8, s20, s18
	s_cselect_b32 s9, s21, s19
	s_lshl_b32 s10, s14, 10
	s_add_u32 s8, s8, s10
	s_addc_u32 s9, s9, 0
	global_load_dwordx4 v[12:15], v2, s[8:9]
	s_add_i32 s14, s14, s86
	s_cmp_ge_i32 s14, 0xa000
	s_cbranch_scc1 .Lpb_ld_done
	s_cmpk_gt_i32 s14, 0x1fff
	s_cselect_b32 s8, s20, s18
	s_cselect_b32 s9, s21, s19
	s_lshl_b32 s10, s14, 10
	s_add_u32 s8, s8, s10
	s_addc_u32 s9, s9, 0
	global_load_dwordx4 v[16:19], v2, s[8:9]
.Lpb_ld_done:
	s_waitcnt vmcnt(0)
	s_mov_b32 s14, s6
	s_cmp_ge_i32 s14, 0xa000
	s_cbranch_scc1 .Lpb_st_done
	s_lshl_b32 s10, s14, 9
	v_lshl_add_u64 v[20:21], v[0:1], 0, s[10:11]
	v_cvt_pk_bf16_f32 v22, v4, v5
	v_cvt_pk_bf16_f32 v23, v6, v7
	global_store_dwordx2 v[20:21], v[22:23], off
	s_add_i32 s14, s14, s86
	s_cmp_ge_i32 s14, 0xa000
	s_cbranch_scc1 .Lpb_st_done
	s_lshl_b32 s10, s14, 9
	v_lshl_add_u64 v[20:21], v[0:1], 0, s[10:11]
	v_cvt_pk_bf16_f32 v22, v8, v9
	v_cvt_pk_bf16_f32 v23, v10, v11
	global_store_dwordx2 v[20:21], v[22:23], off
	s_add_i32 s14, s14, s86
	s_cmp_ge_i32 s14, 0xa000
	s_cbranch_scc1 .Lpb_st_done
	s_lshl_b32 s10, s14, 9
	v_lshl_add_u64 v[20:21], v[0:1], 0, s[10:11]
	v_cvt_pk_bf16_f32 v22, v12, v13
	v_cvt_pk_bf16_f32 v23, v14, v15
	global_store_dwordx2 v[20:21], v[22:23], off
	s_add_i32 s14, s14, s86
	s_cmp_ge_i32 s14, 0xa000
	s_cbranch_scc1 .Lpb_st_done
	s_lshl_b32 s10, s14, 9
	v_lshl_add_u64 v[20:21], v[0:1], 0, s[10:11]
	v_cvt_pk_bf16_f32 v22, v16, v17
	v_cvt_pk_bf16_f32 v23, v18, v19
	global_store_dwordx2 v[20:21], v[22:23], off
.Lpb_st_done:
	s_lshl_b32 s14, s86, 2
	s_add_i32 s6, s6, s14
	s_cmp_lt_i32 s6, 0xa000
	s_cbranch_scc1 .Lpb_batch
